# RWKV scan chunk loops: exposed single ds_read round trips removed (two late reads issued with the earlier batch into dead registers; six operand reads of the last four MFMAs issued together with count
# baseline (speedup 1.0000x reference)
; template <bool PA> ...
;     ...
;             float rv[8], kk[8], av[8], kd[8], lw[8]; u32x4_t tld = (u32x4_t){0u, 0u, 0u, 0u}, vraw = (u32x4_t){0u, 0u, 0u, 0u};
;             {
;                 const size_t row = cbase + (d ? 63 - j : j);
;                 asm volatile("" ::: "memory");
;                 if (haveT && tlow) tld = *(const u32x4_t*)(tbuf + ((size_t)strm * NCHA + p) * 2304 + tunit * 8);
;                 *(u32x4_t*)(MAT(4) + j * 72 + c8) = *(const u32x4_t*)(HWb + row * 128 + d * 64 + c8);
;                 *(u32x4_t*)(MAT(5) + j * 72 + c8) = *(const u32x4_t*)(HAb + row * 128 + d * 64 + c8);
;                 const u32x4_t rw = *(const u32x4_t*)(Rb + row * 1024 + hc8), kw = *(const u32x4_t*)(Kb + row * 1024 + hc8), vw = *(const u32x4_t*)(Vb + row * 1024 + hc8);
;                 __syncthreads();
;                 { f32x4_t za[2], xa[2]; za[0] = (f32x4_t){0.f, 0.f, 0.f, 0.f}; za[1] = za[0]; xa[0] = za[0]; xa[1] = za[0];
;                   mm2(za, MAT(4), w2T, mt, ntb, r16, kq); mm2(xa, MAT(5), a2T, mt, ntb, r16, kq);
; #pragma unroll
;                   for (int i = 0; i < 2; ++i)
; #pragma unroll
;                       for (int e = 0; e < 4; ++e) { zbuf[(16 * mt + 4 * kq + e) * 64 + 16 * (ntb + i) + r16] = za[i][e]; abuf[(16 * mt + 4 * kq + e) * 64 + 16 * (ntb + i) + r16] = xa[i][e]; } }
;                 __syncthreads();
.LBB0_153:
	s_nop 0
	s_waitcnt vmcnt(2)
	ds_write_b128 v91, v[232:235] offset:36864
	ds_write_b128 v91, v[236:239] offset:46080
	v_mov_b32_e32 v10, v228
	v_mov_b32_e32 v11, v229
	v_mov_b32_e32 v12, v230
	v_mov_b32_e32 v13, v231
	v_mov_b32_e32 v18, v240
	v_mov_b32_e32 v19, v241
	v_mov_b32_e32 v20, v242
	v_mov_b32_e32 v21, v243
	v_mov_b32_e32 v22, v244
	v_mov_b32_e32 v23, v245
	v_mov_b32_e32 v24, v246
	v_mov_b32_e32 v25, v247
	v_mov_b32_e32 v14, v248
	v_mov_b32_e32 v15, v249
	v_mov_b32_e32 v16, v250
	v_mov_b32_e32 v17, v251
	s_and_b64 s[0:1], vcc, exec
	s_cselect_b32 s0, s12, s18
	s_cselect_b32 s1, 64, 0xffffffc0
	v_lshl_add_u32 v80, s0, 6, v130
	v_ashrrev_i32_e32 v81, 31, v80
	s_add_i32 s0, s12, 1
	s_cmp_lt_i32 s0, s13
	s_cselect_b32 s1, s1, 0
	v_add_u32_e32 v226, s1, v80
	s_and_saveexec_b64 s[0:1], s[36:37]
	global_load_dwordx4 v[228:231], v[78:79], off
	s_or_b64 exec, exec, s[0:1]
	v_ashrrev_i32_e32 v227, 31, v226
	v_lshlrev_b64 v[224:225], 8, v[226:227]
	v_lshl_add_u64 v[222:223], v[66:67], 0, v[224:225]
	global_load_dwordx4 v[232:235], v[222:223], off
	v_lshl_add_u64 v[222:223], v[68:69], 0, v[224:225]
	global_load_dwordx4 v[236:239], v[222:223], off
	v_lshlrev_b64 v[224:225], 11, v[226:227]
	v_lshl_add_u64 v[222:223], v[70:71], 0, v[224:225]
	global_load_dwordx4 v[240:243], v[222:223], off
	v_lshl_add_u64 v[222:223], v[72:73], 0, v[224:225]
	global_load_dwordx4 v[244:247], v[222:223], off
	v_lshl_add_u64 v[222:223], v[74:75], 0, v[224:225]
	global_load_dwordx4 v[248:251], v[222:223], off
	s_waitcnt lgkmcnt(0)
	s_barrier
	ds_read_b128 v[178:181], v92 offset:36864
	ds_read_b128 v[182:185], v93
	ds_read_b128 v[186:189], v93 offset:2304
	ds_read_b128 v[190:193], v92 offset:36928
	ds_read_b128 v[204:207], v93 offset:64
	ds_read_b128 v[208:211], v93 offset:2368
	ds_read_b128 v[212:215], v92 offset:46080
	ds_read_b128 v[216:219], v94
	ds_read_b128 v[220:223], v94 offset:2304
	ds_read_b128 v[224:227], v92 offset:46144
	s_nop 0
	s_nop 0
	s_nop 0
	s_waitcnt lgkmcnt(8)
	v_mfma_f32_16x16x32_bf16 v[30:33], v[178:181], v[182:185], 0
	ds_read_b128 v[182:185], v94 offset:64
	s_nop 0
	v_lshlrev_b32_e32 v0, 16, v18
	s_waitcnt lgkmcnt(8)
	v_mfma_f32_16x16x32_bf16 v[26:29], v[178:181], v[186:189], 0
	ds_read_b128 v[178:181], v94 offset:2368
	s_nop 0
	s_nop 0
	v_and_b32_e32 v131, 0xffff0000, v18
	s_nop 0
	v_and_b32_e32 v162, 0xffff0000, v24
	s_waitcnt lgkmcnt(7)
	v_mfma_f32_16x16x32_bf16 v[30:33], v[190:193], v[204:207], v[30:33]
	s_nop 0
	v_lshlrev_b32_e32 v141, 16, v21
	v_and_b32_e32 v143, 0xffff0000, v21
	s_waitcnt lgkmcnt(6)
	v_mfma_f32_16x16x32_bf16 v[26:29], v[190:193], v[208:211], v[26:29]
	s_nop 0
	s_nop 0
	s_nop 0
	v_lshlrev_b32_e32 v158, 16, v25
	s_waitcnt lgkmcnt(4)
	v_mfma_f32_16x16x32_bf16 v[38:41], v[212:215], v[216:219], 0
	v_and_b32_e32 v154, 0xffff0000, v25
	s_waitcnt lgkmcnt(3)
	v_mfma_f32_16x16x32_bf16 v[34:37], v[212:215], v[220:223], 0
	s_nop 0
	s_nop 0
	s_waitcnt lgkmcnt(1)
	v_mfma_f32_16x16x32_bf16 v[38:41], v[224:227], v[182:185], v[38:41]
	s_nop 0
	s_waitcnt lgkmcnt(0)
	v_mfma_f32_16x16x32_bf16 v[34:37], v[224:227], v[178:181], v[34:37]
	s_nop 4
	ds_write2st64_b32 v119, v30, v38 offset1:64
	ds_write2st64_b32 v120, v31, v39 offset1:64
	ds_write2st64_b32 v121, v32, v40 offset1:64
	ds_write2st64_b32 v122, v33, v41 offset1:64
	ds_write2st64_b32 v123, v26, v34 offset1:64
	ds_write2st64_b32 v124, v27, v35 offset1:64
	ds_write2st64_b32 v125, v28, v36 offset1:64
	ds_write2st64_b32 v126, v29, v37 offset1:64
	s_waitcnt lgkmcnt(0)
	s_barrier
; __device__ __forceinline__ float sigmoidf_(float x) { return __builtin_amdgcn_rcpf(1.0f + __expf(-x)); }
; template <bool PA> ...
;     ...
;                 float ss = 0.f, bsum = 0.f;
; #pragma unroll
;                 for (int e = 0; e < 8; ++e) { kk[e] = kv[e] * cst[128 + c8 + e]; ss += kk[e] * kk[e]; }
;                 ss += __shfl_xor(ss, 1); ss += __shfl_xor(ss, 2); ss += __shfl_xor(ss, 4);
;                 const float inv = rsqrtf(fmaxf(ss, 1e-24f));
; #pragma unroll
;                 for (int e = 0; e < 8; ++e) { av[e] = sigmoidf_(aa[e]); lw[e] = -0.6065306597f * sigmoidf_(z[e]); kd[e] = kv[e] * (1.0f + (av[e] - 1.0f) * cst[192 + c8 + e]); kk[e] *= inv; bsum += rv[e] * kd[e] * cst[256 + c8 + e]; }
;                 bsum += __shfl_xor(bsum, 1); bsum += __shfl_xor(bsum, 2); bsum += __shfl_xor(bsum, 4);
;                 if (!PA && part == 0) beta[((size_t)d * SLAB + row) * 16 + head] = bsum;
	v_lshlrev_b32_e32 v39, 16, v22
	v_and_b32_e32 v36, 0xffff0000, v22
	v_lshlrev_b32_e32 v133, 16, v19
	v_and_b32_e32 v135, 0xffff0000, v19
	v_lshlrev_b32_e32 v35, 16, v23
	v_and_b32_e32 v34, 0xffff0000, v23
	v_lshlrev_b32_e32 v137, 16, v20
	v_and_b32_e32 v139, 0xffff0000, v20
	v_lshlrev_b32_e32 v38, 16, v24
	ds_read_b128 v[18:21], v95
	ds_read_b128 v[22:25], v95 offset:16
	ds_read_b128 v[144:147], v95 offset:16384
	ds_read_b128 v[148:151], v95 offset:16400
	ds_read_b128 v[26:29], v96
	ds_read_b128 v[30:33], v96 offset:16
	ds_read_b128 v[164:167], v96 offset:256
	ds_read_b128 v[168:171], v96 offset:272
	s_waitcnt lgkmcnt(1)
	v_add_f32_e32 v153, v144, v164
	s_waitcnt lgkmcnt(0)
	v_add_f32_e32 v37, v148, v168
	v_add_f32_e32 v152, v145, v165
	v_add_f32_e32 v164, v149, v169
	v_add_f32_e32 v41, v146, v166
	v_add_f32_e32 v161, v150, v170
	v_add_f32_e32 v40, v147, v167
	v_add_f32_e32 v157, v151, v171
	ds_read_b128 v[144:147], v96 offset:512
	ds_read_b128 v[148:151], v96 offset:528
	ds_read_b128 v[168:171], v96 offset:768
	ds_read_b128 v[172:175], v96 offset:1024
	ds_read_b128 v[178:181], v96 offset:784
	ds_read_b128 v[182:185], v96 offset:1040
	s_waitcnt lgkmcnt(5)
	v_mul_f32_e32 v134, v145, v36
	v_mul_f32_e32 v132, v144, v39
	v_mul_f32_e32 v155, v134, v134
	v_fmac_f32_e32 v155, v132, v132
	v_mul_f32_e32 v136, v146, v35
	v_fmac_f32_e32 v155, v136, v136
	v_mul_f32_e32 v138, v147, v34
	v_fmac_f32_e32 v155, v138, v138
	s_waitcnt lgkmcnt(4)
	v_mul_f32_e32 v140, v148, v38
	v_and_b32_e32 v147, 64, v198
	v_fmac_f32_e32 v155, v140, v140
	v_mul_f32_e32 v142, v149, v162
	v_xor_b32_e32 v146, 1, v198
	v_add_u32_e32 v147, 64, v147
	v_fmac_f32_e32 v155, v142, v142
	v_mul_f32_e32 v144, v150, v158
	v_cmp_lt_i32_e64 s[92:93], v146, v147
	v_fmac_f32_e32 v155, v144, v144
	v_mul_f32_e32 v145, v151, v154
	v_cndmask_b32_e64 v146, v198, v146, s[92:93]
	v_fmac_f32_e32 v155, v145, v145
	v_lshlrev_b32_e32 v146, 2, v146
	s_nop 1
	v_mov_b32_dpp v148, v155 quad_perm:[1,0,3,2] row_mask:0xf bank_mask:0xf
	v_xor_b32_e32 v149, 2, v198
	v_cmp_lt_i32_e64 s[92:93], v149, v147
	s_waitcnt lgkmcnt(0)
	v_add_f32_e32 v148, v155, v148
	v_cndmask_b32_e64 v149, v198, v149, s[92:93]
	v_lshlrev_b32_e32 v166, 2, v149
	s_nop 1
	v_mov_b32_dpp v149, v148 quad_perm:[2,3,0,1] row_mask:0xf bank_mask:0xf
	s_waitcnt lgkmcnt(0)
	v_add_f32_e32 v149, v148, v149
	v_xor_b32_e32 v148, 4, v198
	v_cmp_lt_i32_e64 s[92:93], v148, v147
	s_nop 1
	v_cndmask_b32_e64 v147, v198, v148, s[92:93]
	v_mul_f32_e32 v148, 0xbfb8aa3b, v153
	v_exp_f32_e32 v148, v148
	v_lshlrev_b32_e32 v147, 2, v147
	s_nop 1
	v_mov_b32_dpp v150, v149 row_half_mirror row_mask:0xf bank_mask:0xf
	v_add_f32_e32 v148, 1.0, v148
	v_rcp_f32_e32 v148, v148
	s_nop 0
	v_add_f32_e32 v151, -1.0, v148
	v_fma_f32 v151, v151, v168, 1.0
	v_mul_f32_e32 v151, v151, v39
	v_mul_f32_e32 v39, v151, v0
	v_fma_f32 v167, v172, v39, 0
	v_mul_f32_e32 v39, 0xbfb8aa3b, v152
	v_exp_f32_e32 v39, v39
	s_nop 0
	v_add_f32_e32 v39, 1.0, v39
	v_rcp_f32_e32 v152, v39
	s_nop 0
	v_add_f32_e32 v39, -1.0, v152
	v_fma_f32 v39, v39, v169, 1.0
	v_mul_f32_e32 v153, v39, v36
	v_mul_f32_e32 v36, v153, v131
	v_fmac_f32_e32 v167, v173, v36
	v_mul_f32_e32 v36, 0xbfb8aa3b, v41
	v_exp_f32_e32 v36, v36
	s_nop 0
	v_add_f32_e32 v36, 1.0, v36
	v_rcp_f32_e32 v155, v36
	s_nop 0
	v_add_f32_e32 v36, -1.0, v155
	v_fma_f32 v36, v36, v170, 1.0
	v_mul_f32_e32 v156, v36, v35
	v_mul_f32_e32 v35, v156, v133
	v_fmac_f32_e32 v167, v174, v35
	v_mul_f32_e32 v35, 0xbfb8aa3b, v40
	v_exp_f32_e32 v35, v35
	s_nop 0
	v_add_f32_e32 v35, 1.0, v35
	v_rcp_f32_e32 v159, v35
	s_nop 0
	v_add_f32_e32 v35, -1.0, v159
	v_fma_f32 v35, v35, v171, 1.0
	v_mul_f32_e32 v160, v35, v34
	v_mul_f32_e32 v34, v160, v135
	v_fmac_f32_e32 v167, v175, v34
	v_mul_f32_e32 v34, 0xbfb8aa3b, v37
	v_exp_f32_e32 v34, v34
	s_nop 0
	v_add_f32_e32 v34, 1.0, v34
	v_rcp_f32_e32 v163, v34
	v_mov_b64_e32 v[34:35], v[178:179]
	v_mov_b64_e32 v[36:37], v[180:181]
	v_add_f32_e32 v39, -1.0, v163
	s_waitcnt lgkmcnt(0)
	v_fma_f32 v34, v39, v34, 1.0
	v_mul_f32_e32 v165, v34, v38
	v_mov_b64_e32 v[38:39], v[182:183]
	v_mov_b64_e32 v[40:41], v[184:185]
	v_mul_f32_e32 v34, v165, v137
	s_waitcnt lgkmcnt(0)
	v_fmac_f32_e32 v167, v38, v34
	v_mul_f32_e32 v34, 0xbfb8aa3b, v164
	v_exp_f32_e32 v34, v34
	s_nop 0
	v_add_f32_e32 v34, 1.0, v34
	v_rcp_f32_e32 v38, v34
	s_nop 0
	v_add_f32_e32 v34, -1.0, v38
	v_fma_f32 v34, v34, v35, 1.0
	v_mul_f32_e32 v162, v34, v162
	v_mul_f32_e32 v34, v162, v139
	v_fmac_f32_e32 v167, v39, v34
	v_mul_f32_e32 v34, 0xbfb8aa3b, v161
	v_exp_f32_e32 v34, v34
	s_nop 0
	v_add_f32_e32 v34, 1.0, v34
	v_rcp_f32_e32 v39, v34
	s_nop 0
	v_add_f32_e32 v34, -1.0, v39
	v_fma_f32 v34, v34, v36, 1.0
	v_mul_f32_e32 v36, v34, v158
	v_mul_f32_e32 v34, v36, v141
	v_fmac_f32_e32 v167, v40, v34
	v_mul_f32_e32 v34, 0xbfb8aa3b, v157
	v_exp_f32_e32 v34, v34
	s_nop 0
	v_add_f32_e32 v34, 1.0, v34
	v_rcp_f32_e32 v40, v34
	s_nop 0
	v_add_f32_e32 v34, -1.0, v40
	v_fma_f32 v34, v34, v37, 1.0
	v_mul_f32_e32 v37, v34, v154
	v_mul_f32_e32 v34, v37, v143
	v_fmac_f32_e32 v167, v41, v34
	s_nop 1
	v_mov_b32_dpp v34, v167 quad_perm:[1,0,3,2] row_mask:0xf bank_mask:0xf
	s_waitcnt lgkmcnt(0)
	v_add_f32_e32 v34, v167, v34
	s_nop 1
	v_mov_b32_dpp v35, v34 quad_perm:[2,3,0,1] row_mask:0xf bank_mask:0xf
	s_waitcnt lgkmcnt(0)
	v_add_f32_e32 v34, v34, v35
	s_nop 1
	v_mov_b32_dpp v35, v34 row_half_mirror row_mask:0xf bank_mask:0xf
	s_and_saveexec_b64 s[0:1], s[44:45]
	s_cbranch_execz .LBB0_157
	v_lshl_add_u64 v[146:147], s[24:25], 0, v[80:81]
	v_lshlrev_b64 v[146:147], 6, v[146:147]
	v_lshl_add_u64 v[146:147], s[20:21], 0, v[146:147]
	s_waitcnt lgkmcnt(0)
	v_add_f32_e32 v34, v34, v35
	global_store_dword v[146:147], v34, off

; template <bool PA> ...
;     ...
;             mm2(Xacc, MAT(10), MAT(6), mt, ntb, r16, kq);
;             st_tr(MAT(7), Xacc, mt, ntb, r16, kq);
;             if (PA) st_tr(MAT(11), X2acc, mt, ntb, r16, kq);
;             __syncthreads();
;             tmp[0] = z4; tmp[1] = z4; mm2(tmp, Tm, MAT(7), mt, ntb, r16, kq);
;             st_tr(MAT(8), tmp, mt, ntb, r16, kq);
;             if (PA) { tmp[0] = z4; tmp[1] = z4; mm2(tmp, MAT(3), MAT(11), mt, ntb, r16, kq); st_tr(MAT(12), tmp, mt, ntb, r16, kq); }
;             __syncthreads();
;             if (!PA) { mm2(Yacc, MAT(11), MAT(8), mt, ntb, r16, kq); mm2(Yacc, MAT(12), MAT(6), mt, ntb, r16, kq);
;             st_rm(MAT(7), Yacc, mt, ntb, r16, kq); }
;             if (PA) mm2(S2acc, MAT(12), MAT(4), mt, ntb, r16, kq);
;             mm2(Sacc, MAT(8), MAT(4), mt, ntb, r16, kq); mm2(Sacc, MAT(6), MAT(5), mt, ntb, r16, kq);
; #pragma unroll
;             for (int i = 0; i < 2; ++i) { const float wk = wc[16 * (ntb + i) + r16];
; #pragma unroll
;                 for (int e = 0; e < 4; ++e) { Sacc[i][e] *= wk; S2acc[i][e] *= wk; } }
;             __syncthreads();
.LBB0_245:
	s_or_b64 exec, exec, s[12:13]
	ds_read_b128 v[26:29], v128
	ds_read_b128 v[30:33], v118 offset:55296
	ds_read_b128 v[186:189], v118 offset:57600
	ds_read_b128 v[190:193], v128 offset:64
	ds_read_b128 v[204:207], v118 offset:55360
	ds_read_b128 v[208:211], v118 offset:57664
	s_add_i32 s20, s20, 1
	s_add_i32 s24, s24, -1
	v_lshl_add_u64 v[100:101], v[100:101], 0, s[34:35]
	s_cmp_ge_i32 s20, s21
	s_waitcnt lgkmcnt(4)
	v_mfma_f32_16x16x32_bf16 v[22:25], v[26:29], v[30:33], v[22:25]
	s_waitcnt lgkmcnt(3)
	v_mfma_f32_16x16x32_bf16 v[18:21], v[26:29], v[186:189], v[18:21]
	s_waitcnt lgkmcnt(1)
	v_mfma_f32_16x16x32_bf16 v[22:25], v[190:193], v[204:207], v[22:25]
	s_waitcnt lgkmcnt(0)
	v_mfma_f32_16x16x32_bf16 v[18:21], v[190:193], v[208:211], v[18:21]
	s_nop 4
	v_cvt_pk_bf16_f32 v22, v22, v23
	v_cvt_pk_bf16_f32 v23, v24, v25
	ds_write_b64 v127, v[22:23] offset:64512
	v_cvt_pk_bf16_f32 v18, v18, v19
	v_cvt_pk_bf16_f32 v19, v20, v21
	ds_write_b64 v129, v[18:19]
	v_cvt_pk_bf16_f32 v18, v46, v47
	v_cvt_pk_bf16_f32 v19, v48, v49
	ds_write_b64 v130, v[18:19]
	v_cvt_pk_bf16_f32 v18, v42, v43
	v_cvt_pk_bf16_f32 v19, v44, v45
	ds_write_b64 v130, v[18:19] offset:2304
	s_waitcnt lgkmcnt(0)
	s_barrier
	ds_read_b128 v[186:189], v69 offset:27648
	ds_read_b128 v[190:193], v118 offset:64512
	ds_read_b128 v[204:207], v123
	ds_read_b128 v[208:211], v69 offset:27712
	ds_read_b128 v[212:215], v118 offset:64576
	ds_read_b128 v[216:219], v124
	ds_read_b128 v[220:223], v69 offset:27648
	ds_read_b128 v[224:227], v132
	s_nop 0
	s_nop 0
	s_nop 0
	s_waitcnt lgkmcnt(6)
	v_mfma_f32_16x16x32_bf16 v[22:25], v[186:189], v[190:193], 0
	ds_read_b128 v[190:193], v132 offset:2304
	s_waitcnt lgkmcnt(6)
	v_mfma_f32_16x16x32_bf16 v[18:21], v[186:189], v[204:207], 0
	ds_read_b128 v[186:189], v69 offset:27712
	ds_read_b128 v[204:207], v132 offset:64
	s_nop 0
	s_nop 0
	s_waitcnt lgkmcnt(6)
	v_mfma_f32_16x16x32_bf16 v[22:25], v[208:211], v[212:215], v[22:25]
	ds_read_b128 v[212:215], v132 offset:2368
	s_nop 0
	s_waitcnt lgkmcnt(6)
	v_mfma_f32_16x16x32_bf16 v[18:21], v[208:211], v[216:219], v[18:21]
	s_nop 4
	v_cvt_pk_bf16_f32 v22, v22, v23
	v_cvt_pk_bf16_f32 v23, v24, v25
	ds_write_b64 v131, v[22:23]
	v_cvt_pk_bf16_f32 v18, v18, v19
	v_cvt_pk_bf16_f32 v19, v20, v21
	ds_write_b64 v131, v[18:19] offset:2304
	s_nop 0
	s_nop 0
	s_nop 0
	s_waitcnt lgkmcnt(0)
	v_mfma_f32_16x16x32_bf16 v[22:25], v[220:223], v[224:227], 0
	s_waitcnt lgkmcnt(0)
	v_mfma_f32_16x16x32_bf16 v[18:21], v[220:223], v[190:193], 0
	s_nop 0
	s_nop 0
	s_waitcnt lgkmcnt(0)
	v_mfma_f32_16x16x32_bf16 v[22:25], v[186:189], v[204:207], v[22:25]
	s_nop 0
	s_waitcnt lgkmcnt(0)
	v_mfma_f32_16x16x32_bf16 v[18:21], v[186:189], v[212:215], v[18:21]
	s_nop 4
	v_cvt_pk_bf16_f32 v22, v22, v23
	v_cvt_pk_bf16_f32 v23, v24, v25
	ds_write_b64 v133, v[22:23]
	v_cvt_pk_bf16_f32 v18, v18, v19
	v_cvt_pk_bf16_f32 v19, v20, v21
	ds_write_b64 v133, v[18:19] offset:2304
	s_waitcnt lgkmcnt(0)
	s_barrier
	ds_read_b128 v[186:189], v134
	ds_read_b128 v[190:193], v118 offset:36864
	ds_read_b128 v[204:207], v118 offset:39168
	ds_read_b128 v[208:211], v134 offset:64
	ds_read_b128 v[212:215], v118 offset:36928
	ds_read_b128 v[216:219], v118 offset:39232
	ds_read_b128 v[220:223], v125
	ds_read_b128 v[224:227], v125 offset:64
	s_nop 0
	s_nop 0
	s_nop 0
	s_waitcnt lgkmcnt(6)
	v_mfma_f32_16x16x32_bf16 v[10:13], v[186:189], v[190:193], v[10:13]
	s_waitcnt lgkmcnt(5)
	v_mfma_f32_16x16x32_bf16 v[14:17], v[186:189], v[204:207], v[14:17]
	ds_read_b128 v[186:189], v69 offset:55296
	s_nop 0
	s_nop 0
	s_nop 0
	s_waitcnt lgkmcnt(4)
	v_mfma_f32_16x16x32_bf16 v[10:13], v[208:211], v[212:215], v[10:13]
	s_waitcnt lgkmcnt(3)
	v_mfma_f32_16x16x32_bf16 v[14:17], v[208:211], v[216:219], v[14:17]
	ds_read_b128 v[208:211], v118 offset:46080
	s_nop 0
	s_waitcnt lgkmcnt(3)
	v_mfma_f32_16x16x32_bf16 v[2:5], v[220:223], v[190:193], v[2:5]
	ds_read_b128 v[190:193], v118 offset:48384
	v_mfma_f32_16x16x32_bf16 v[6:9], v[220:223], v[204:207], v[6:9]
	v_mov_b32_e32 v26, v204
	v_mov_b32_e32 v27, v205
	v_mov_b32_e32 v28, v206
	v_mov_b32_e32 v29, v207
	ds_read_b128 v[204:207], v69 offset:55360
	ds_read_b128 v[220:223], v118 offset:46144
	s_nop 0
	s_waitcnt lgkmcnt(5)
	v_mfma_f32_16x16x32_bf16 v[2:5], v[224:227], v[212:215], v[2:5]
	v_mov_b32_e32 v30, v212
	v_mov_b32_e32 v31, v213
	v_mov_b32_e32 v32, v214
	v_mov_b32_e32 v33, v215
	ds_read_b128 v[212:215], v118 offset:48448
	v_mfma_f32_16x16x32_bf16 v[6:9], v[224:227], v[216:219], v[6:9]
	v_mov_b32_e32 v34, v216
	v_mov_b32_e32 v35, v217
	v_mov_b32_e32 v36, v218
	v_mov_b32_e32 v37, v219
	s_nop 0
	s_nop 0
	s_waitcnt lgkmcnt(4)
	v_mfma_f32_16x16x32_bf16 v[2:5], v[186:189], v[208:211], v[2:5]
	s_nop 0
	s_waitcnt lgkmcnt(3)
	v_mfma_f32_16x16x32_bf16 v[6:9], v[186:189], v[190:193], v[6:9]
	s_nop 0
	s_nop 0
	ds_read_b32 v0, v157
	s_waitcnt lgkmcnt(0)
	v_pk_mul_f32 v[12:13], v[12:13], v[0:1] op_sel_hi:[1,0]
	v_mfma_f32_16x16x32_bf16 v[2:5], v[204:207], v[220:223], v[2:5]
	s_nop 0
	v_pk_mul_f32 v[10:11], v[10:11], v[0:1] op_sel_hi:[1,0]
	s_waitcnt lgkmcnt(0)
	v_mfma_f32_16x16x32_bf16 v[6:9], v[204:207], v[212:215], v[6:9]
	v_mov_b32_e32 v18, v204
	v_mov_b32_e32 v19, v205
	v_mov_b32_e32 v20, v206
	v_mov_b32_e32 v21, v207
	v_mov_b32_e32 v22, v212
	v_mov_b32_e32 v23, v213
	v_mov_b32_e32 v24, v214
	v_mov_b32_e32 v25, v215
	s_nop 3
	v_mul_f32_e64 v2, v2, v0
	v_mul_f32_e64 v3, v3, v0
	v_pk_mul_f32 v[4:5], v[4:5], v[0:1] op_sel_hi:[1,0]
	ds_read_b32 v0, v158
	s_waitcnt lgkmcnt(0)
	s_barrier
	v_pk_mul_f32 v[6:7], v[6:7], v[0:1] op_sel_hi:[1,0]
	v_pk_mul_f32 v[8:9], v[8:9], v[0:1] op_sel_hi:[1,0]
	v_pk_mul_f32 v[16:17], v[16:17], v[0:1] op_sel_hi:[1,0]
	v_pk_mul_f32 v[14:15], v[14:15], v[0:1] op_sel_hi:[1,0]
	s_cbranch_scc1 .LBB0_193
	v_mov_b32_e32 v0, v9
	s_branch .LBB0_213
